# attention tile loop: next-tile global loads issued after the first QK MFMA pair instead of ahead of the first wait
# baseline (speedup 1.0000x reference)
.LBB0_175:
	s_barrier
	ds_read_b128 v[162:165], v104
	ds_read_b128 v[166:169], v104 offset:64
	ds_read_b128 v[170:173], v104 offset:128
	ds_read_b128 v[174:177], v104 offset:3584
	ds_read_b128 v[178:181], v104 offset:3648
	ds_read_b128 v[182:185], v104 offset:3712
	ds_read_b128 v[186:189], v104 offset:7168
	ds_read_b128 v[214:217], v104 offset:7232
	ds_read_b128 v[218:221], v104 offset:7296
	ds_read_b128 v[222:225], v104 offset:10752
	ds_read_b128 v[226:229], v104 offset:10816
	ds_read_b128 v[230:233], v104 offset:10880
	s_and_b32 s21, s7, 15
	s_cbranch_scc0 .Lattn_refresh
	s_waitcnt lgkmcnt(9)
	v_mfma_f32_16x16x32_bf16 v[92:95], v[162:165], v[0:3], v[148:151]
	v_mfma_f32_16x16x32_bf16 v[76:79], v[162:165], v[8:11], v[152:155]
	global_load_dwordx4 v[72:75], v[136:137], off
	global_load_dwordx4 v[68:71], v[134:135], off
	global_load_dwordx4 v[64:67], v[132:133], off
	ds_read_b64 v[234:235], v147 offset:14336
	ds_read_b64 v[236:237], v147 offset:14368
	v_mfma_f32_16x16x32_bf16 v[92:95], v[166:169], v[4:7], v[92:95]
	v_mfma_f32_16x16x32_bf16 v[76:79], v[166:169], v[12:15], v[76:79]
	ds_read_b64 v[238:239], v147 offset:14400
	ds_read_b64 v[240:241], v147 offset:14432
	v_mfma_f32_16x16x32_bf16 v[92:95], v[170:173], v[16:19], v[92:95]
	v_mfma_f32_16x16x32_bf16 v[76:79], v[170:173], v[20:23], v[76:79]
	ds_read_b64 v[242:243], v147 offset:16640
	ds_read_b64 v[244:245], v147 offset:16672
	s_waitcnt lgkmcnt(12)
	v_mfma_f32_16x16x32_bf16 v[96:99], v[174:177], v[0:3], v[148:151]
	v_mfma_f32_16x16x32_bf16 v[80:83], v[174:177], v[8:11], v[152:155]
	ds_read_b64 v[246:247], v147 offset:16704
	v_mfma_f32_16x16x32_bf16 v[96:99], v[178:181], v[4:7], v[96:99]
	v_mfma_f32_16x16x32_bf16 v[80:83], v[178:181], v[12:15], v[80:83]
	ds_read_b64 v[248:249], v147 offset:16736
	v_mfma_f32_16x16x32_bf16 v[96:99], v[182:185], v[16:19], v[96:99]
	v_mfma_f32_16x16x32_bf16 v[80:83], v[182:185], v[20:23], v[80:83]
	ds_read_b64 v[162:163], v147 offset:18944
	s_waitcnt lgkmcnt(12)
	v_mfma_f32_16x16x32_bf16 v[100:103], v[186:189], v[0:3], v[148:151]
	v_mfma_f32_16x16x32_bf16 v[84:87], v[186:189], v[8:11], v[152:155]
	ds_read_b64 v[164:165], v147 offset:18976
	v_mfma_f32_16x16x32_bf16 v[100:103], v[214:217], v[4:7], v[100:103]
	v_mfma_f32_16x16x32_bf16 v[84:87], v[214:217], v[12:15], v[84:87]
	ds_read_b64 v[166:167], v147 offset:19008
	v_mfma_f32_16x16x32_bf16 v[100:103], v[218:221], v[16:19], v[100:103]
	v_mfma_f32_16x16x32_bf16 v[84:87], v[218:221], v[20:23], v[84:87]
	ds_read_b64 v[168:169], v147 offset:19040
	s_waitcnt lgkmcnt(12)
	v_mfma_f32_16x16x32_bf16 v[104:107], v[222:225], v[0:3], v[148:151]
	v_mfma_f32_16x16x32_bf16 v[88:91], v[222:225], v[8:11], v[152:155]
	ds_read_b64 v[170:171], v147 offset:21248
	v_mfma_f32_16x16x32_bf16 v[104:107], v[226:229], v[4:7], v[104:107]
	v_mfma_f32_16x16x32_bf16 v[88:91], v[226:229], v[12:15], v[88:91]
	ds_read_b64 v[172:173], v147 offset:21280
	v_mfma_f32_16x16x32_bf16 v[104:107], v[230:233], v[16:19], v[104:107]
	v_mfma_f32_16x16x32_bf16 v[88:91], v[230:233], v[20:23], v[88:91]
	s_waitcnt lgkmcnt(13)
	ds_read_b64 v[174:175], v147 offset:21312
	ds_read_b64 v[176:177], v147 offset:21344

.Lattn_refresh:
	s_waitcnt lgkmcnt(9)
	v_mfma_f32_16x16x32_bf16 v[92:95], v[162:165], v[0:3], 0
	v_mfma_f32_16x16x32_bf16 v[76:79], v[162:165], v[8:11], 0
	global_load_dwordx4 v[72:75], v[136:137], off
	global_load_dwordx4 v[68:71], v[134:135], off
	global_load_dwordx4 v[64:67], v[132:133], off
	ds_read_b64 v[234:235], v147 offset:14336
	ds_read_b64 v[236:237], v147 offset:14368
	v_mfma_f32_16x16x32_bf16 v[92:95], v[166:169], v[4:7], v[92:95]
	v_mfma_f32_16x16x32_bf16 v[76:79], v[166:169], v[12:15], v[76:79]
	ds_read_b64 v[238:239], v147 offset:14400
	ds_read_b64 v[240:241], v147 offset:14432
	v_mfma_f32_16x16x32_bf16 v[92:95], v[170:173], v[16:19], v[92:95]
	v_mfma_f32_16x16x32_bf16 v[76:79], v[170:173], v[20:23], v[76:79]
	ds_read_b64 v[242:243], v147 offset:16640
	ds_read_b64 v[244:245], v147 offset:16672
	s_waitcnt lgkmcnt(12)
	v_mfma_f32_16x16x32_bf16 v[96:99], v[174:177], v[0:3], 0
	v_mfma_f32_16x16x32_bf16 v[80:83], v[174:177], v[8:11], 0
	ds_read_b64 v[246:247], v147 offset:16704
	v_mfma_f32_16x16x32_bf16 v[96:99], v[178:181], v[4:7], v[96:99]
	v_mfma_f32_16x16x32_bf16 v[80:83], v[178:181], v[12:15], v[80:83]
	ds_read_b64 v[248:249], v147 offset:16736
	v_mfma_f32_16x16x32_bf16 v[96:99], v[182:185], v[16:19], v[96:99]
	v_mfma_f32_16x16x32_bf16 v[80:83], v[182:185], v[20:23], v[80:83]
	ds_read_b64 v[162:163], v147 offset:18944
	s_waitcnt lgkmcnt(12)
	v_mfma_f32_16x16x32_bf16 v[100:103], v[186:189], v[0:3], 0
	v_mfma_f32_16x16x32_bf16 v[84:87], v[186:189], v[8:11], 0
	ds_read_b64 v[164:165], v147 offset:18976
	v_mfma_f32_16x16x32_bf16 v[100:103], v[214:217], v[4:7], v[100:103]
	v_mfma_f32_16x16x32_bf16 v[84:87], v[214:217], v[12:15], v[84:87]
	ds_read_b64 v[166:167], v147 offset:19008
	v_mfma_f32_16x16x32_bf16 v[100:103], v[218:221], v[16:19], v[100:103]
	v_mfma_f32_16x16x32_bf16 v[84:87], v[218:221], v[20:23], v[84:87]
	ds_read_b64 v[168:169], v147 offset:19040
	s_waitcnt lgkmcnt(12)
	v_mfma_f32_16x16x32_bf16 v[104:107], v[222:225], v[0:3], 0
	v_mfma_f32_16x16x32_bf16 v[88:91], v[222:225], v[8:11], 0
	ds_read_b64 v[170:171], v147 offset:21248
	v_mfma_f32_16x16x32_bf16 v[104:107], v[226:229], v[4:7], v[104:107]
	v_mfma_f32_16x16x32_bf16 v[88:91], v[226:229], v[12:15], v[88:91]
	ds_read_b64 v[172:173], v147 offset:21280
	v_mfma_f32_16x16x32_bf16 v[104:107], v[230:233], v[16:19], v[104:107]
	v_mfma_f32_16x16x32_bf16 v[88:91], v[230:233], v[20:23], v[88:91]
	s_waitcnt lgkmcnt(13)
	ds_read_b64 v[174:175], v147 offset:21312
	ds_read_b64 v[176:177], v147 offset:21344
	s_nop 7
	v_max_f32_e32 v127, v93, v93
	v_max_f32_e32 v129, v92, v92
	v_max_f32_e32 v127, v129, v127
	v_max_f32_e32 v129, v95, v95
	v_max_f32_e32 v131, v94, v94
	v_max_f32_e32 v129, v131, v129
	v_max_f32_e32 v131, v99, v99
	v_max_f32_e32 v147, v98, v98
	v_max_f32_e32 v131, v147, v131
	v_max3_f32 v131, v96, v97, v131
	v_max3_f32 v127, v127, v129, v131
	v_max_f32_e32 v129, v103, v103
	v_max_f32_e32 v131, v102, v102
	v_max_f32_e32 v129, v131, v129
	v_max_f32_e32 v131, v107, v107
	v_max_f32_e32 v147, v106, v106
	v_max_f32_e32 v131, v147, v131
	v_max3_f32 v129, v100, v101, v129
	v_max3_f32 v131, v104, v105, v131
	v_max3_f32 v127, v127, v129, v131
	ds_bpermute_b32 v129, v145, v127
	s_waitcnt lgkmcnt(0)
	v_max_f32_e32 v129, v129, v129
	v_max_f32_e32 v127, v127, v129
	ds_bpermute_b32 v129, v144, v127
	s_waitcnt lgkmcnt(0)
	v_max3_f32 v127, v130, v127, v129
	v_sub_f32_e32 v129, v130, v127
	v_exp_f32_e32 v130, v129
	s_nop 0
	v_pk_mul_f32 v[62:63], v[62:63], v[130:131] op_sel_hi:[1,0]
	v_pk_mul_f32 v[60:61], v[60:61], v[130:131] op_sel_hi:[1,0]
	v_pk_mul_f32 v[54:55], v[54:55], v[130:131] op_sel_hi:[1,0]
	v_pk_mul_f32 v[52:53], v[52:53], v[130:131] op_sel_hi:[1,0]
	v_pk_mul_f32 v[46:47], v[46:47], v[130:131] op_sel_hi:[1,0]
	v_pk_mul_f32 v[44:45], v[44:45], v[130:131] op_sel_hi:[1,0]
	v_pk_mul_f32 v[38:39], v[38:39], v[130:131] op_sel_hi:[1,0]
	v_pk_mul_f32 v[36:37], v[36:37], v[130:131] op_sel_hi:[1,0]
	v_pk_mul_f32 v[30:31], v[30:31], v[130:131] op_sel_hi:[1,0]
	v_pk_mul_f32 v[28:29], v[28:29], v[130:131] op_sel_hi:[1,0]
	v_mov_b32_e32 v130, v127
	v_xor_b32_e32 v148, 0x80000000, v127
	v_xor_b32_e32 v149, 0x80000000, v127
	v_xor_b32_e32 v150, 0x80000000, v127
	v_xor_b32_e32 v151, 0x80000000, v127
	v_max_f32_e32 v127, v77, v77
	v_max_f32_e32 v129, v76, v76
	v_max_f32_e32 v127, v129, v127
	v_max_f32_e32 v129, v79, v79
	v_max_f32_e32 v131, v78, v78
	v_max_f32_e32 v129, v131, v129
	v_max_f32_e32 v131, v83, v83
	v_max_f32_e32 v147, v82, v82
	v_max_f32_e32 v131, v147, v131
	v_max3_f32 v131, v80, v81, v131
	v_max3_f32 v127, v127, v129, v131
	v_max_f32_e32 v129, v87, v87
	v_max_f32_e32 v131, v86, v86
	v_max_f32_e32 v129, v131, v129
	v_max_f32_e32 v131, v91, v91
	v_max_f32_e32 v147, v90, v90
	v_max_f32_e32 v131, v147, v131
	v_max3_f32 v129, v84, v85, v129
	v_max3_f32 v131, v88, v89, v131
	v_max3_f32 v127, v127, v129, v131
	ds_bpermute_b32 v129, v145, v127
	s_waitcnt lgkmcnt(0)
	v_max_f32_e32 v129, v129, v129
	v_max_f32_e32 v127, v127, v129
	ds_bpermute_b32 v129, v144, v127
	s_waitcnt lgkmcnt(0)
	v_max3_f32 v131, v128, v127, v129
	v_sub_f32_e32 v127, v128, v131
	v_exp_f32_e32 v128, v127
	s_nop 0
	v_pk_mul_f32 v[58:59], v[58:59], v[128:129] op_sel_hi:[1,0]
	v_pk_mul_f32 v[56:57], v[56:57], v[128:129] op_sel_hi:[1,0]
	v_pk_mul_f32 v[50:51], v[50:51], v[128:129] op_sel_hi:[1,0]
	v_pk_mul_f32 v[48:49], v[48:49], v[128:129] op_sel_hi:[1,0]
	v_pk_mul_f32 v[42:43], v[42:43], v[128:129] op_sel_hi:[1,0]
	v_pk_mul_f32 v[40:41], v[40:41], v[128:129] op_sel_hi:[1,0]
	v_pk_mul_f32 v[34:35], v[34:35], v[128:129] op_sel_hi:[1,0]
	v_pk_mul_f32 v[32:33], v[32:33], v[128:129] op_sel_hi:[1,0]
	v_pk_mul_f32 v[26:27], v[26:27], v[128:129] op_sel_hi:[1,0]
	v_pk_mul_f32 v[24:25], v[24:25], v[128:129] op_sel_hi:[1,0]
	v_mov_b32_e32 v128, v131
	v_xor_b32_e32 v152, 0x80000000, v131
	v_xor_b32_e32 v153, 0x80000000, v131
	v_xor_b32_e32 v154, 0x80000000, v131
	v_xor_b32_e32 v155, 0x80000000, v131
	v_pk_add_f32 v[92:93], v[92:93], v[130:131] op_sel_hi:[1,0] neg_lo:[0,1] neg_hi:[0,1]
	v_pk_add_f32 v[94:95], v[94:95], v[130:131] op_sel_hi:[1,0] neg_lo:[0,1] neg_hi:[0,1]
	v_pk_add_f32 v[96:97], v[96:97], v[130:131] op_sel_hi:[1,0] neg_lo:[0,1] neg_hi:[0,1]
	v_pk_add_f32 v[98:99], v[98:99], v[130:131] op_sel_hi:[1,0] neg_lo:[0,1] neg_hi:[0,1]
	v_pk_add_f32 v[100:101], v[100:101], v[130:131] op_sel_hi:[1,0] neg_lo:[0,1] neg_hi:[0,1]
	v_pk_add_f32 v[102:103], v[102:103], v[130:131] op_sel_hi:[1,0] neg_lo:[0,1] neg_hi:[0,1]
	v_pk_add_f32 v[104:105], v[104:105], v[130:131] op_sel_hi:[1,0] neg_lo:[0,1] neg_hi:[0,1]
	v_pk_add_f32 v[106:107], v[106:107], v[130:131] op_sel_hi:[1,0] neg_lo:[0,1] neg_hi:[0,1]
	v_pk_add_f32 v[76:77], v[76:77], v[128:129] op_sel_hi:[1,0] neg_lo:[0,1] neg_hi:[0,1]
	v_pk_add_f32 v[78:79], v[78:79], v[128:129] op_sel_hi:[1,0] neg_lo:[0,1] neg_hi:[0,1]
	v_pk_add_f32 v[80:81], v[80:81], v[128:129] op_sel_hi:[1,0] neg_lo:[0,1] neg_hi:[0,1]
	v_pk_add_f32 v[82:83], v[82:83], v[128:129] op_sel_hi:[1,0] neg_lo:[0,1] neg_hi:[0,1]
	v_pk_add_f32 v[84:85], v[84:85], v[128:129] op_sel_hi:[1,0] neg_lo:[0,1] neg_hi:[0,1]
	v_pk_add_f32 v[86:87], v[86:87], v[128:129] op_sel_hi:[1,0] neg_lo:[0,1] neg_hi:[0,1]
	v_pk_add_f32 v[88:89], v[88:89], v[128:129] op_sel_hi:[1,0] neg_lo:[0,1] neg_hi:[0,1]
	v_pk_add_f32 v[90:91], v[90:91], v[128:129] op_sel_hi:[1,0] neg_lo:[0,1] neg_hi:[0,1]
	s_branch .Lattn_sm
